# NA 6, all LRU summary units in the P2 queue
# baseline (speedup 1.0000x reference)
.Lq_cont:
	s_mov_b32 s3, s97
	s_cmp_eq_u32 s32, 0x100
	s_cbranch_scc1 .Li8_s1
	s_cmpk_lt_i32 s97, 0x70
	s_cselect_b32 s3, 0, 0x230
	s_add_i32 s3, s3, s97

.Li8_en:
	s_cmpk_lt_i32 s6, 0x70
	s_cbranch_scc0 .Li8_clsB
	s_mul_i32 s5, s53, 0x70
	s_add_i32 s5, s5, s6
	s_cmpk_lt_i32 s53, 6
	s_cselect_b32 s5, s5, 0x3e0
	s_branch .Li8_join
.Li8_clsB:
	s_mul_i32 s5, s53, 0x90
	s_add_i32 s5, s5, s6
	s_add_i32 s5, s5, 0x230
